# cross-half row max via v_permlane32_swap instead of ds_bpermute; tile address multiply moved to SALU
# speedup vs baseline: 1.0018x; 1.0018x over previous
; #define LOAD_TILE(KR, VR, tl) do { KR = *(const GAS u32x4*)(kg + (size_t)(tl) * 64 * LDH); VR = *(const GAS u32x4*)(vg + (size_t)(tl) * 64 * LDH); } while (0)
; template <int MODE> ...
;     ...
;     for (int it = 0; it < ntiles && !stop; it += 2) {
;         LOAD_TILE(kreg, vreg, TILE_OF(min(it + 2, ntiles - 1)));
;         COMPUTE_TILE(TILE_OF(it), 0);
.LBB0_824:
	s_add_i32 s12, s13, 2
	s_min_i32 s4, s12, s10
	s_mul_i32 s4, s4, 0x62000
	s_mov_b32 s5, 0
	v_lshl_add_u64 v[34:35], s[4:5], 0, v[98:99]
	global_load_dwordx4 v[90:93], v[34:35], off offset:768
	global_load_dwordx4 v[94:97], v[34:35], off offset:1536
	s_cmp_gt_i32 s13, s9
	s_cbranch_scc1 .LBB0_832
	ds_read_b128 v[34:37], v110
	ds_read_b128 v[38:41], v110 offset:32
	ds_read_b128 v[42:45], v110 offset:64
	ds_read_b128 v[46:49], v110 offset:96
	ds_read_b128 v[116:119], v113
	ds_read_b128 v[120:123], v113 offset:32
	ds_read_b128 v[124:127], v113 offset:64
	ds_read_b128 v[182:185], v113 offset:96
	ds_read_b128 v[50:53], v110 offset:128
	ds_read_b128 v[54:57], v110 offset:160
	ds_read_b128 v[58:61], v110 offset:192
	ds_read_b128 v[62:65], v110 offset:224
	ds_read_b128 v[186:189], v113 offset:4608
	ds_read_b128 v[190:193], v113 offset:4640
	ds_read_b128 v[242:245], v113 offset:4672
	ds_read_b128 v[246:249], v113 offset:4704
	v_sub_f32_e32 v1, v105, v112
	s_waitcnt lgkmcnt(12)
	v_sub_f32_e32 v34, v1, v34
	v_sub_f32_e32 v35, v1, v35
	v_sub_f32_e32 v36, v1, v36
	v_sub_f32_e32 v37, v1, v37
	v_sub_f32_e32 v38, v1, v38
	v_sub_f32_e32 v39, v1, v39
	v_sub_f32_e32 v40, v1, v40
	v_sub_f32_e32 v41, v1, v41
	v_sub_f32_e32 v42, v1, v42
	v_sub_f32_e32 v43, v1, v43
	v_sub_f32_e32 v44, v1, v44
	v_sub_f32_e32 v45, v1, v45
	v_sub_f32_e32 v46, v1, v46
	v_sub_f32_e32 v47, v1, v47
	v_sub_f32_e32 v48, v1, v48
	v_sub_f32_e32 v49, v1, v49
	s_waitcnt vmcnt(4) lgkmcnt(4)
	s_nop 0
	v_mfma_f32_32x32x16_bf16 v[34:49], v[116:119], v[66:69], v[34:49]
	v_sub_f32_e32 v50, v1, v50
	v_sub_f32_e32 v51, v1, v51
	v_sub_f32_e32 v52, v1, v52
	v_sub_f32_e32 v53, v1, v53
	s_waitcnt lgkmcnt(4)
	v_mfma_f32_32x32x16_bf16 v[34:49], v[120:123], v[70:73], v[34:49]
	v_sub_f32_e32 v54, v1, v54
	v_sub_f32_e32 v55, v1, v55
	v_sub_f32_e32 v56, v1, v56
	v_sub_f32_e32 v57, v1, v57
	s_waitcnt lgkmcnt(4)
	v_mfma_f32_32x32x16_bf16 v[34:49], v[124:127], v[74:77], v[34:49]
	v_sub_f32_e32 v58, v1, v58
	v_sub_f32_e32 v59, v1, v59
	v_sub_f32_e32 v60, v1, v60
	v_sub_f32_e32 v61, v1, v61
	s_waitcnt lgkmcnt(0)
	v_mfma_f32_32x32x16_bf16 v[34:49], v[182:185], v[78:81], v[34:49]
	v_sub_f32_e32 v62, v1, v62
	v_sub_f32_e32 v63, v1, v63
	v_sub_f32_e32 v64, v1, v64
	v_sub_f32_e32 v65, v1, v65
	s_nop 1
	v_mfma_f32_32x32x16_bf16 v[50:65], v[186:189], v[66:69], v[50:65]
	ds_read_b64_tr_b16 v[198:199], v108 offset:9216
	ds_read_b64_tr_b16 v[200:201], v108 offset:10368
	ds_read_b64_tr_b16 v[202:203], v108 offset:11520
	ds_read_b64_tr_b16 v[204:205], v108 offset:12672
	v_mfma_f32_32x32x16_bf16 v[50:65], v[190:193], v[70:73], v[50:65]
	ds_read_b64_tr_b16 v[206:207], v108 offset:13824
	ds_read_b64_tr_b16 v[208:209], v108 offset:14976
	ds_read_b64_tr_b16 v[210:211], v108 offset:16128
	ds_read_b64_tr_b16 v[212:213], v108 offset:17280
	v_mfma_f32_32x32x16_bf16 v[50:65], v[242:245], v[74:77], v[50:65]
	ds_read_b64_tr_b16 v[214:215], v108 offset:9280
	ds_read_b64_tr_b16 v[216:217], v108 offset:10432
	ds_read_b64_tr_b16 v[218:219], v108 offset:11584
	ds_read_b64_tr_b16 v[220:221], v108 offset:12736
	v_mfma_f32_32x32x16_bf16 v[50:65], v[246:249], v[78:81], v[50:65]
	ds_read_b64_tr_b16 v[234:235], v108 offset:13888
	ds_read_b64_tr_b16 v[236:237], v108 offset:15040
	ds_read_b64_tr_b16 v[238:239], v108 offset:16192
	ds_read_b64_tr_b16 v[240:241], v108 offset:17344
	s_nop 1
	s_cmp_lg_u32 s9, s13
	s_cbranch_scc1 .LBB0_827
	v_add_u32_e32 v104, 0xffffffa5, v111
	v_add_u32_e32 v1, 0xffffff85, v111
	v_cmp_le_i32_e32 vcc, v104, v102
	s_nop 7
	v_cndmask_b32_e32 v50, v232, v50, vcc
	v_cmp_lt_i32_e32 vcc, v1, v102
	s_nop 1
	v_cndmask_b32_e32 v35, v232, v35, vcc
	v_cmp_le_i32_e32 vcc, v1, v102
	v_add_u32_e32 v1, 0xffffffa6, v111
	s_nop 0
	v_cndmask_b32_e32 v34, v232, v34, vcc
	v_cmp_le_i32_e32 vcc, v1, v102
	v_add_u32_e32 v1, 0xffffff87, v111
	s_nop 0
	v_cndmask_b32_e32 v51, v232, v51, vcc
	v_cmp_le_i32_e32 vcc, v1, v102
	v_add_u32_e32 v1, 0xffffffa7, v111
	s_nop 0
	v_cndmask_b32_e32 v36, v232, v36, vcc
	v_cmp_le_i32_e32 vcc, v1, v102
	v_add_u32_e32 v1, 0xffffff88, v111
	s_nop 0
	v_cndmask_b32_e32 v52, v232, v52, vcc
	v_cmp_le_i32_e32 vcc, v1, v102
	v_add_u32_e32 v1, 0xffffffa8, v111
	s_nop 0
	v_cndmask_b32_e32 v37, v232, v37, vcc
	v_cmp_le_i32_e32 vcc, v1, v102
	v_add_u32_e32 v1, 0xffffff8d, v111
	s_nop 0
	v_cndmask_b32_e32 v53, v232, v53, vcc
	v_cmp_le_i32_e32 vcc, v1, v102
	v_add_u32_e32 v1, 0xffffffad, v111
	s_nop 0
	v_cndmask_b32_e32 v38, v232, v38, vcc
	v_cmp_le_i32_e32 vcc, v1, v102
	v_add_u32_e32 v1, 0xffffff8e, v111
	s_nop 0
	v_cndmask_b32_e32 v54, v232, v54, vcc
	v_cmp_le_i32_e32 vcc, v1, v102
	v_add_u32_e32 v1, 0xffffffae, v111
	s_nop 0
	v_cndmask_b32_e32 v39, v232, v39, vcc
	v_cmp_le_i32_e32 vcc, v1, v102
	v_add_u32_e32 v1, 0xffffff8f, v111
	s_nop 0
	v_cndmask_b32_e32 v55, v232, v55, vcc
	v_cmp_le_i32_e32 vcc, v1, v102
	v_add_u32_e32 v1, 0xffffffaf, v111
	s_nop 0
	v_cndmask_b32_e32 v40, v232, v40, vcc
	v_cmp_le_i32_e32 vcc, v1, v102
	v_add_u32_e32 v1, 0xffffff90, v111
	s_nop 0
	v_cndmask_b32_e32 v56, v232, v56, vcc
	v_cmp_le_i32_e32 vcc, v1, v102
	v_add_u32_e32 v1, 0xffffffb0, v111
	s_nop 0
	v_cndmask_b32_e32 v41, v232, v41, vcc
	v_cmp_le_i32_e32 vcc, v1, v102
	v_add_u32_e32 v1, 0xffffff95, v111
	s_nop 0
	v_cndmask_b32_e32 v57, v232, v57, vcc
	v_cmp_le_i32_e32 vcc, v1, v102
	v_add_u32_e32 v1, 0xffffffb5, v111
	s_nop 0
	v_cndmask_b32_e32 v42, v232, v42, vcc
	v_cmp_le_i32_e32 vcc, v1, v102
	v_add_u32_e32 v1, 0xffffff96, v111
	s_nop 0
	v_cndmask_b32_e32 v58, v232, v58, vcc
	v_cmp_le_i32_e32 vcc, v1, v102
	v_add_u32_e32 v1, 0xffffffb6, v111
	s_nop 0
	v_cndmask_b32_e32 v43, v232, v43, vcc
	v_cmp_le_i32_e32 vcc, v1, v102
	v_add_u32_e32 v1, 0xffffff97, v111
	s_nop 0
	v_cndmask_b32_e32 v59, v232, v59, vcc
	v_cmp_le_i32_e32 vcc, v1, v102
	v_add_u32_e32 v1, 0xffffffb7, v111
	s_nop 0
	v_cndmask_b32_e32 v44, v232, v44, vcc
	v_cmp_le_i32_e32 vcc, v1, v102
	v_add_u32_e32 v1, 0xffffff98, v111
	s_nop 0
	v_cndmask_b32_e32 v60, v232, v60, vcc
	v_cmp_le_i32_e32 vcc, v1, v102
	v_add_u32_e32 v1, 0xffffffb8, v111
	s_nop 0
	v_cndmask_b32_e32 v45, v232, v45, vcc
	v_cmp_le_i32_e32 vcc, v1, v102
	v_add_u32_e32 v1, 0xffffff9d, v111
	s_nop 0
	v_cndmask_b32_e32 v61, v232, v61, vcc
	v_cmp_le_i32_e32 vcc, v1, v102
	v_add_u32_e32 v1, 0xffffffbd, v111
	s_nop 0
	v_cndmask_b32_e32 v46, v232, v46, vcc
	v_cmp_le_i32_e32 vcc, v1, v102
	v_add_u32_e32 v1, 0xffffff9e, v111
	s_nop 0
	v_cndmask_b32_e32 v62, v232, v62, vcc
	v_cmp_le_i32_e32 vcc, v1, v102
	v_add_u32_e32 v1, 0xffffffbe, v111
	s_nop 0
	v_cndmask_b32_e32 v47, v232, v47, vcc
	v_cmp_le_i32_e32 vcc, v1, v102
	v_add_u32_e32 v1, 0xffffff9f, v111
	s_nop 0
	v_cndmask_b32_e32 v63, v232, v63, vcc
	v_cmp_le_i32_e32 vcc, v1, v102
	v_add_u32_e32 v1, 0xffffffbf, v111
	s_nop 0
	v_cndmask_b32_e32 v48, v232, v48, vcc
	v_cmp_le_i32_e32 vcc, v1, v102
	v_add_u32_e32 v1, 0xffffffa0, v111
	s_nop 0
	v_cndmask_b32_e32 v64, v232, v64, vcc
	v_cmp_le_i32_e32 vcc, v1, v102
	v_subrev_u32_e32 v1, 64, v111
	s_nop 0
	v_cndmask_b32_e32 v49, v232, v49, vcc
	v_cmp_le_i32_e32 vcc, v1, v102
	s_nop 1
	v_cndmask_b32_e32 v65, v232, v65, vcc
.LBB0_827:
	v_max3_f32 v104, v34, v35, v36
	v_max3_f32 v106, v37, v38, v39
	v_max3_f32 v115, v40, v41, v42
	v_max3_f32 v1, v43, v44, v45
	v_max3_f32 v104, v104, v46, v47
	v_max3_f32 v106, v106, v48, v49
	v_max3_f32 v115, v115, v50, v51
	v_max3_f32 v1, v1, v52, v53
	v_max3_f32 v104, v104, v54, v55
	v_max3_f32 v106, v106, v56, v57
	v_max3_f32 v115, v115, v58, v59
	v_max3_f32 v1, v1, v60, v61
	v_max3_f32 v104, v104, v62, v63
	v_max3_f32 v106, v106, v64, v65
	v_max3_f32 v1, v1, v115, s82
	v_max3_f32 v1, v1, v104, v106
	v_mov_b32_e32 v104, v1
	s_xor_b64 s[0:1], s[0:1], -1
	s_nop 0
	v_permlane32_swap_b32_e32 v104, v1
	v_max_f32_e32 v1, v1, v104
	s_and_saveexec_b64 s[4:5], s[0:1]
	s_xor_b64 s[0:1], exec, s[4:5]
	s_cbranch_execnz .LBB0_842
	s_or_saveexec_b64 s[4:5], s[0:1]
	s_mov_b64 s[0:1], 0
	s_xor_b64 exec, exec, s[4:5]
	s_cbranch_execnz .LBB0_845

.LBB0_831:
	v_exp_f32_e32 v34, v34
	v_exp_f32_e32 v35, v35
	v_exp_f32_e32 v36, v36
	v_exp_f32_e32 v37, v37
	v_exp_f32_e32 v38, v38
	v_exp_f32_e32 v39, v39
	v_exp_f32_e32 v40, v40
	v_exp_f32_e32 v41, v41
	v_add_f32_e32 v104, v34, v35
	v_add_f32_e32 v106, v36, v37
	v_add_f32_e32 v104, v104, v38
	v_add_f32_e32 v106, v106, v39
	v_add_f32_e32 v104, v104, v40
	v_add_f32_e32 v106, v106, v41
	v_cvt_pk_bf16_f32 v132, v34, v35
	v_cvt_pk_bf16_f32 v133, v36, v37
	v_cvt_pk_bf16_f32 v134, v38, v39
	v_cvt_pk_bf16_f32 v135, v40, v41
	v_exp_f32_e32 v42, v42
	v_exp_f32_e32 v43, v43
	s_waitcnt lgkmcnt(0)
	v_mfma_f32_32x32x16_bf16 v[18:33], v[198:201], v[132:135], v[18:33]
	v_mfma_f32_32x32x16_bf16 v[2:17], v[214:217], v[132:135], v[2:17]
	v_exp_f32_e32 v44, v44
	v_exp_f32_e32 v45, v45
	v_exp_f32_e32 v46, v46
	v_exp_f32_e32 v47, v47
	v_exp_f32_e32 v48, v48
	v_exp_f32_e32 v49, v49
	v_add_f32_e32 v104, v104, v42
	v_add_f32_e32 v106, v106, v43
	v_add_f32_e32 v104, v104, v44
	v_add_f32_e32 v106, v106, v45
	v_add_f32_e32 v104, v104, v46
	v_add_f32_e32 v106, v106, v47
	v_add_f32_e32 v104, v104, v48
	v_add_f32_e32 v106, v106, v49
	v_cvt_pk_bf16_f32 v148, v42, v43
	v_cvt_pk_bf16_f32 v149, v44, v45
	v_cvt_pk_bf16_f32 v150, v46, v47
	v_cvt_pk_bf16_f32 v151, v48, v49
	v_exp_f32_e32 v50, v50
	v_exp_f32_e32 v51, v51
	v_mfma_f32_32x32x16_bf16 v[18:33], v[202:205], v[148:151], v[18:33]
	v_mfma_f32_32x32x16_bf16 v[2:17], v[218:221], v[148:151], v[2:17]
	v_exp_f32_e32 v52, v52
	v_exp_f32_e32 v53, v53
	v_exp_f32_e32 v54, v54
	v_exp_f32_e32 v55, v55
	v_exp_f32_e32 v56, v56
	v_exp_f32_e32 v57, v57
	v_add_f32_e32 v104, v104, v50
	v_add_f32_e32 v106, v106, v51
	v_add_f32_e32 v104, v104, v52
	v_add_f32_e32 v106, v106, v53
	v_add_f32_e32 v104, v104, v54
	v_add_f32_e32 v106, v106, v55
	v_add_f32_e32 v104, v104, v56
	v_add_f32_e32 v106, v106, v57
	v_cvt_pk_bf16_f32 v156, v50, v51
	v_cvt_pk_bf16_f32 v157, v52, v53
	v_cvt_pk_bf16_f32 v158, v54, v55
	v_cvt_pk_bf16_f32 v159, v56, v57
	v_exp_f32_e32 v58, v58
	v_exp_f32_e32 v59, v59
	v_mfma_f32_32x32x16_bf16 v[18:33], v[206:209], v[156:159], v[18:33]
	v_mfma_f32_32x32x16_bf16 v[2:17], v[234:237], v[156:159], v[2:17]
	v_exp_f32_e32 v60, v60
	v_exp_f32_e32 v61, v61
	v_exp_f32_e32 v62, v62
	v_exp_f32_e32 v63, v63
	v_exp_f32_e32 v64, v64
	v_exp_f32_e32 v65, v65
	v_add_f32_e32 v104, v104, v58
	v_add_f32_e32 v106, v106, v59
	v_add_f32_e32 v104, v104, v60
	v_add_f32_e32 v106, v106, v61
	v_add_f32_e32 v104, v104, v62
	v_add_f32_e32 v106, v106, v63
	v_add_f32_e32 v104, v104, v64
	v_add_f32_e32 v106, v106, v65
	v_cvt_pk_bf16_f32 v172, v58, v59
	v_cvt_pk_bf16_f32 v173, v60, v61
	v_cvt_pk_bf16_f32 v174, v62, v63
	v_cvt_pk_bf16_f32 v175, v64, v65
	v_add_f32_e32 v104, v104, v106
	v_add_f32_e32 v114, v114, v104
	v_mfma_f32_32x32x16_bf16 v[18:33], v[210:213], v[172:175], v[18:33]
	v_mfma_f32_32x32x16_bf16 v[2:17], v[238:241], v[172:175], v[2:17]
.LBB0_832:
	s_add_i32 s4, s13, 3
	s_min_i32 s4, s4, s10
	s_mul_i32 s4, s4, 0x62000
	s_mov_b32 s5, 0
	v_lshl_add_u64 v[34:35], s[4:5], 0, v[98:99]
	s_waitcnt vmcnt(3)
	ds_write_b128 v107, v[82:85] offset:18432
	s_waitcnt vmcnt(2)
	ds_write_b128 v107, v[86:89] offset:27648
	s_waitcnt lgkmcnt(0)
	s_barrier
	global_load_dwordx4 v[82:85], v[34:35], off offset:768
	global_load_dwordx4 v[86:89], v[34:35], off offset:1536
	s_cmp_ge_i32 s13, s9
	s_cbranch_scc1 .LBB0_840
	ds_read_b128 v[34:37], v110 offset:256
	ds_read_b128 v[38:41], v110 offset:288
	ds_read_b128 v[42:45], v110 offset:320
	ds_read_b128 v[46:49], v110 offset:352
	ds_read_b128 v[116:119], v113 offset:18432
	ds_read_b128 v[120:123], v113 offset:18464
	ds_read_b128 v[124:127], v113 offset:18496
	ds_read_b128 v[182:185], v113 offset:18528
	ds_read_b128 v[50:53], v110 offset:384
	ds_read_b128 v[54:57], v110 offset:416
	ds_read_b128 v[58:61], v110 offset:448
	ds_read_b128 v[62:65], v110 offset:480
	ds_read_b128 v[186:189], v113 offset:23040
	ds_read_b128 v[190:193], v113 offset:23072
	ds_read_b128 v[242:245], v113 offset:23104
	ds_read_b128 v[246:249], v113 offset:23136
	v_sub_f32_e32 v1, v105, v112
	s_waitcnt lgkmcnt(12)
	v_sub_f32_e32 v34, v1, v34
	v_sub_f32_e32 v35, v1, v35
	v_sub_f32_e32 v36, v1, v36
	v_sub_f32_e32 v37, v1, v37
	v_sub_f32_e32 v38, v1, v38
	v_sub_f32_e32 v39, v1, v39
	v_sub_f32_e32 v40, v1, v40
	v_sub_f32_e32 v41, v1, v41
	v_sub_f32_e32 v42, v1, v42
	v_sub_f32_e32 v43, v1, v43
	v_sub_f32_e32 v44, v1, v44
	v_sub_f32_e32 v45, v1, v45
	v_sub_f32_e32 v46, v1, v46
	v_sub_f32_e32 v47, v1, v47
	v_sub_f32_e32 v48, v1, v48
	v_sub_f32_e32 v49, v1, v49
	s_waitcnt lgkmcnt(4)
	s_nop 0
	v_mfma_f32_32x32x16_bf16 v[34:49], v[116:119], v[66:69], v[34:49]
	v_sub_f32_e32 v50, v1, v50
	v_sub_f32_e32 v51, v1, v51
	v_sub_f32_e32 v52, v1, v52
	v_sub_f32_e32 v53, v1, v53
	s_waitcnt lgkmcnt(4)
	v_mfma_f32_32x32x16_bf16 v[34:49], v[120:123], v[70:73], v[34:49]
	v_sub_f32_e32 v54, v1, v54
	v_sub_f32_e32 v55, v1, v55
	v_sub_f32_e32 v56, v1, v56
	v_sub_f32_e32 v57, v1, v57
	s_waitcnt lgkmcnt(4)
	v_mfma_f32_32x32x16_bf16 v[34:49], v[124:127], v[74:77], v[34:49]
	v_sub_f32_e32 v58, v1, v58
	v_sub_f32_e32 v59, v1, v59
	v_sub_f32_e32 v60, v1, v60
	v_sub_f32_e32 v61, v1, v61
	s_waitcnt lgkmcnt(0)
	v_mfma_f32_32x32x16_bf16 v[34:49], v[182:185], v[78:81], v[34:49]
	v_sub_f32_e32 v62, v1, v62
	v_sub_f32_e32 v63, v1, v63
	v_sub_f32_e32 v64, v1, v64
	v_sub_f32_e32 v65, v1, v65
	s_nop 1
	v_mfma_f32_32x32x16_bf16 v[50:65], v[186:189], v[66:69], v[50:65]
	ds_read_b64_tr_b16 v[198:199], v108 offset:27648
	ds_read_b64_tr_b16 v[200:201], v108 offset:28800
	ds_read_b64_tr_b16 v[202:203], v108 offset:29952
	ds_read_b64_tr_b16 v[204:205], v108 offset:31104
	v_mfma_f32_32x32x16_bf16 v[50:65], v[190:193], v[70:73], v[50:65]
	ds_read_b64_tr_b16 v[206:207], v108 offset:32256
	ds_read_b64_tr_b16 v[208:209], v108 offset:33408
	ds_read_b64_tr_b16 v[210:211], v108 offset:34560
	ds_read_b64_tr_b16 v[212:213], v108 offset:35712
	v_mfma_f32_32x32x16_bf16 v[50:65], v[242:245], v[74:77], v[50:65]
	ds_read_b64_tr_b16 v[214:215], v108 offset:27712
	ds_read_b64_tr_b16 v[216:217], v108 offset:28864
	ds_read_b64_tr_b16 v[218:219], v108 offset:30016
	ds_read_b64_tr_b16 v[220:221], v108 offset:31168
	v_mfma_f32_32x32x16_bf16 v[50:65], v[246:249], v[78:81], v[50:65]
	ds_read_b64_tr_b16 v[234:235], v108 offset:32320
	ds_read_b64_tr_b16 v[236:237], v108 offset:33472
	ds_read_b64_tr_b16 v[238:239], v108 offset:34624
	ds_read_b64_tr_b16 v[240:241], v108 offset:35776
	s_nop 1
	s_cmp_lg_u32 s11, s13
	s_cbranch_scc1 .LBB0_835
	v_subrev_u32_e32 v104, 27, v111
	v_subrev_u32_e32 v1, 59, v111
	v_cmp_le_i32_e32 vcc, v104, v102
	s_nop 7
	v_cndmask_b32_e32 v50, v232, v50, vcc
	v_cmp_lt_i32_e32 vcc, v1, v102
	s_nop 1
	v_cndmask_b32_e32 v35, v232, v35, vcc
	v_cmp_le_i32_e32 vcc, v1, v102
	v_subrev_u32_e32 v1, 26, v111
	s_nop 0
	v_cndmask_b32_e32 v34, v232, v34, vcc
	v_cmp_le_i32_e32 vcc, v1, v102
	v_subrev_u32_e32 v1, 57, v111
	s_nop 0
	v_cndmask_b32_e32 v51, v232, v51, vcc
	v_cmp_le_i32_e32 vcc, v1, v102
	v_subrev_u32_e32 v1, 25, v111
	s_nop 0
	v_cndmask_b32_e32 v36, v232, v36, vcc
	v_cmp_le_i32_e32 vcc, v1, v102
	v_subrev_u32_e32 v1, 56, v111
	s_nop 0
	v_cndmask_b32_e32 v52, v232, v52, vcc
	v_cmp_le_i32_e32 vcc, v1, v102
	v_subrev_u32_e32 v1, 24, v111
	s_nop 0
	v_cndmask_b32_e32 v37, v232, v37, vcc
	v_cmp_le_i32_e32 vcc, v1, v102
	v_subrev_u32_e32 v1, 51, v111
	s_nop 0
	v_cndmask_b32_e32 v53, v232, v53, vcc
	v_cmp_le_i32_e32 vcc, v1, v102
	v_subrev_u32_e32 v1, 19, v111
	s_nop 0
	v_cndmask_b32_e32 v38, v232, v38, vcc
	v_cmp_le_i32_e32 vcc, v1, v102
	v_subrev_u32_e32 v1, 50, v111
	s_nop 0
	v_cndmask_b32_e32 v54, v232, v54, vcc
	v_cmp_le_i32_e32 vcc, v1, v102
	v_subrev_u32_e32 v1, 18, v111
	s_nop 0
	v_cndmask_b32_e32 v39, v232, v39, vcc
	v_cmp_le_i32_e32 vcc, v1, v102
	v_subrev_u32_e32 v1, 49, v111
	s_nop 0
	v_cndmask_b32_e32 v55, v232, v55, vcc
	v_cmp_le_i32_e32 vcc, v1, v102
	v_subrev_u32_e32 v1, 17, v111
	s_nop 0
	v_cndmask_b32_e32 v40, v232, v40, vcc
	v_cmp_le_i32_e32 vcc, v1, v102
	v_subrev_u32_e32 v1, 48, v111
	s_nop 0
	v_cndmask_b32_e32 v56, v232, v56, vcc
	v_cmp_le_i32_e32 vcc, v1, v102
	v_add_u32_e32 v1, -16, v111
	s_nop 0
	v_cndmask_b32_e32 v41, v232, v41, vcc
	v_cmp_le_i32_e32 vcc, v1, v102
	v_subrev_u32_e32 v1, 43, v111
	s_nop 0
	v_cndmask_b32_e32 v57, v232, v57, vcc
	v_cmp_le_i32_e32 vcc, v1, v102
	v_add_u32_e32 v1, -11, v111
	s_nop 0
	v_cndmask_b32_e32 v42, v232, v42, vcc
	v_cmp_le_i32_e32 vcc, v1, v102
	v_subrev_u32_e32 v1, 42, v111
	s_nop 0
	v_cndmask_b32_e32 v58, v232, v58, vcc
	v_cmp_le_i32_e32 vcc, v1, v102
	v_add_u32_e32 v1, -10, v111
	s_nop 0
	v_cndmask_b32_e32 v43, v232, v43, vcc
	v_cmp_le_i32_e32 vcc, v1, v102
	v_subrev_u32_e32 v1, 41, v111
	s_nop 0
	v_cndmask_b32_e32 v59, v232, v59, vcc
	v_cmp_le_i32_e32 vcc, v1, v102
	v_add_u32_e32 v1, -9, v111
	s_nop 0
	v_cndmask_b32_e32 v44, v232, v44, vcc
	v_cmp_le_i32_e32 vcc, v1, v102
	v_subrev_u32_e32 v1, 40, v111
	s_nop 0
	v_cndmask_b32_e32 v60, v232, v60, vcc
	v_cmp_le_i32_e32 vcc, v1, v102
	v_add_u32_e32 v1, -8, v111
	s_nop 0
	v_cndmask_b32_e32 v45, v232, v45, vcc
	v_cmp_le_i32_e32 vcc, v1, v102
	v_subrev_u32_e32 v1, 35, v111
	s_nop 0
	v_cndmask_b32_e32 v61, v232, v61, vcc
	v_cmp_le_i32_e32 vcc, v1, v102
	v_add_u32_e32 v1, -3, v111
	s_nop 0
	v_cndmask_b32_e32 v46, v232, v46, vcc
	v_cmp_le_i32_e32 vcc, v1, v102
	v_subrev_u32_e32 v1, 34, v111
	s_nop 0
	v_cndmask_b32_e32 v62, v232, v62, vcc
	v_cmp_le_i32_e32 vcc, v1, v102
	v_add_u32_e32 v1, -2, v111
	s_nop 0
	v_cndmask_b32_e32 v47, v232, v47, vcc
	v_cmp_le_i32_e32 vcc, v1, v102
	v_subrev_u32_e32 v1, 33, v111
	s_nop 0
	v_cndmask_b32_e32 v63, v232, v63, vcc
	v_cmp_le_i32_e32 vcc, v1, v102
	v_add_u32_e32 v1, -1, v111
	s_nop 0
	v_cndmask_b32_e32 v48, v232, v48, vcc
	v_cmp_le_i32_e32 vcc, v1, v102
	v_subrev_u32_e32 v1, 32, v111
	s_nop 0
	v_cndmask_b32_e32 v64, v232, v64, vcc
	v_cmp_le_i32_e32 vcc, v1, v102
	s_nop 1
	v_cndmask_b32_e32 v49, v232, v49, vcc
	v_cmp_le_i32_e32 vcc, v111, v102
	s_nop 1
	v_cndmask_b32_e32 v65, v232, v65, vcc

; #define LOAD_TILE(KR, VR, tl) do { KR = *(const GAS u32x4*)(kg + (size_t)(tl) * 64 * LDH); VR = *(const GAS u32x4*)(vg + (size_t)(tl) * 64 * LDH); } while (0)
; template <int MODE> ...
;     ...
;         LOAD_TILE(kreg, vreg, TILE_OF(min(it + 2, ntiles - 1)));
;         COMPUTE_TILE(TILE_OF(it), 0);
.LBB0_920:
	s_add_i32 s19, s23, 2
	s_min_i32 s14, s19, s18
	s_mul_i32 s12, s14, 0x62000
	s_mov_b32 s13, 0
	v_lshl_add_u64 v[34:35], s[12:13], 0, v[102:103]
	s_mul_i32 s12, s14, 0x62000
	s_mov_b32 s13, 0
	v_lshl_add_u64 v[36:37], s[12:13], 0, v[104:105]
	global_load_dwordx4 v[90:93], v[34:35], off
	global_load_dwordx4 v[94:97], v[36:37], off
	s_cmp_gt_i32 s23, s17
	s_cbranch_scc1 .LBB0_926
	ds_read_b64 v[34:35], v109
	ds_read_b128 v[118:121], v113
	ds_read_b128 v[122:125], v113 offset:32
	ds_read_b128 v[126:129], v113 offset:64
	ds_read_b128 v[130:133], v113 offset:96
	ds_read_b128 v[182:185], v113 offset:4608
	ds_read_b128 v[186:189], v113 offset:4640
	ds_read_b128 v[190:193], v113 offset:4672
	ds_read_b128 v[242:245], v113 offset:4704
	v_sub_f32_e32 v1, 0, v112
	s_xor_b64 s[10:11], s[10:11], -1
	s_waitcnt lgkmcnt(8)
	v_lshrrev_b64 v[114:115], v100, v[34:35]
	v_lshrrev_b64 v[116:117], v106, v[34:35]
	v_bfe_i32 v34, v114, 0, 1
	v_bfe_i32 v35, v114, 1, 1
	v_bfe_i32 v36, v114, 2, 1
	v_bfe_i32 v37, v114, 3, 1
	v_bfe_i32 v38, v114, 8, 1
	v_bfe_i32 v39, v114, 9, 1
	v_bfe_i32 v40, v114, 10, 1
	v_bfe_i32 v41, v114, 11, 1
	v_bfe_i32 v42, v114, 16, 1
	v_bfe_i32 v43, v114, 17, 1
	v_bfe_i32 v44, v114, 18, 1
	v_bfe_i32 v45, v114, 19, 1
	v_bfe_i32 v46, v114, 24, 1
	v_bfe_i32 v47, v114, 25, 1
	v_bfe_i32 v48, v114, 26, 1
	v_bfe_i32 v49, v114, 27, 1
	v_bfi_b32 v34, v34, v1, v232
	v_bfi_b32 v35, v35, v1, v232
	v_bfi_b32 v36, v36, v1, v232
	v_bfi_b32 v37, v37, v1, v232
	v_bfi_b32 v38, v38, v1, v232
	v_bfi_b32 v39, v39, v1, v232
	v_bfi_b32 v40, v40, v1, v232
	v_bfi_b32 v41, v41, v1, v232
	v_bfi_b32 v42, v42, v1, v232
	v_bfi_b32 v43, v43, v1, v232
	v_bfi_b32 v44, v44, v1, v232
	v_bfi_b32 v45, v45, v1, v232
	v_bfi_b32 v46, v46, v1, v232
	v_bfi_b32 v47, v47, v1, v232
	v_bfi_b32 v48, v48, v1, v232
	v_bfi_b32 v49, v49, v1, v232
	s_waitcnt vmcnt(4) lgkmcnt(4)
	s_nop 0
	v_mfma_f32_32x32x16_bf16 v[34:49], v[118:121], v[74:77], v[34:49]
	v_bfe_i32 v50, v116, 0, 1
	v_bfe_i32 v51, v116, 1, 1
	v_bfe_i32 v52, v116, 2, 1
	v_bfe_i32 v53, v116, 3, 1
	v_bfe_i32 v54, v116, 8, 1
	v_bfe_i32 v55, v116, 9, 1
	v_bfe_i32 v56, v116, 10, 1
	v_bfe_i32 v57, v116, 11, 1
	s_waitcnt lgkmcnt(4)
	v_mfma_f32_32x32x16_bf16 v[34:49], v[122:125], v[66:69], v[34:49]
	v_bfe_i32 v58, v116, 16, 1
	v_bfe_i32 v59, v116, 17, 1
	v_bfe_i32 v60, v116, 18, 1
	v_bfe_i32 v61, v116, 19, 1
	v_bfe_i32 v62, v116, 24, 1
	v_bfe_i32 v63, v116, 25, 1
	v_bfe_i32 v64, v116, 26, 1
	v_bfe_i32 v65, v116, 27, 1
	s_waitcnt lgkmcnt(4)
	v_mfma_f32_32x32x16_bf16 v[34:49], v[126:129], v[70:73], v[34:49]
	v_bfi_b32 v50, v50, v1, v232
	v_bfi_b32 v51, v51, v1, v232
	v_bfi_b32 v52, v52, v1, v232
	v_bfi_b32 v53, v53, v1, v232
	v_bfi_b32 v54, v54, v1, v232
	v_bfi_b32 v55, v55, v1, v232
	v_bfi_b32 v56, v56, v1, v232
	v_bfi_b32 v57, v57, v1, v232
	s_waitcnt lgkmcnt(0)
	v_mfma_f32_32x32x16_bf16 v[34:49], v[130:133], v[78:81], v[34:49]
	v_bfi_b32 v58, v58, v1, v232
	v_bfi_b32 v59, v59, v1, v232
	v_bfi_b32 v60, v60, v1, v232
	v_bfi_b32 v61, v61, v1, v232
	v_bfi_b32 v62, v62, v1, v232
	v_bfi_b32 v63, v63, v1, v232
	v_bfi_b32 v64, v64, v1, v232
	v_bfi_b32 v65, v65, v1, v232
	s_nop 1
	v_mfma_f32_32x32x16_bf16 v[50:65], v[182:185], v[74:77], v[50:65]
	ds_read_b64_tr_b16 v[198:199], v107 offset:9216
	ds_read_b64_tr_b16 v[200:201], v107 offset:10368
	ds_read_b64_tr_b16 v[202:203], v107 offset:11520
	ds_read_b64_tr_b16 v[204:205], v107 offset:12672
	v_mfma_f32_32x32x16_bf16 v[50:65], v[186:189], v[66:69], v[50:65]
	ds_read_b64_tr_b16 v[206:207], v107 offset:13824
	ds_read_b64_tr_b16 v[208:209], v107 offset:14976
	ds_read_b64_tr_b16 v[210:211], v107 offset:16128
	ds_read_b64_tr_b16 v[212:213], v107 offset:17280
	v_mfma_f32_32x32x16_bf16 v[50:65], v[190:193], v[70:73], v[50:65]
	ds_read_b64_tr_b16 v[214:215], v107 offset:9280
	ds_read_b64_tr_b16 v[216:217], v107 offset:10432
	ds_read_b64_tr_b16 v[218:219], v107 offset:11584
	ds_read_b64_tr_b16 v[220:221], v107 offset:12736
	v_mfma_f32_32x32x16_bf16 v[50:65], v[242:245], v[78:81], v[50:65]
	ds_read_b64_tr_b16 v[234:235], v107 offset:13888
	ds_read_b64_tr_b16 v[236:237], v107 offset:15040
	ds_read_b64_tr_b16 v[238:239], v107 offset:16192
	ds_read_b64_tr_b16 v[240:241], v107 offset:17344
	s_nop 1
	v_max3_f32 v108, v34, v35, v36
	v_max3_f32 v110, v37, v38, v39
	v_max3_f32 v114, v40, v41, v42
	v_max3_f32 v1, v43, v44, v45
	v_max3_f32 v108, v108, v46, v47
	v_max3_f32 v110, v110, v48, v49
	v_max3_f32 v114, v114, v50, v51
	v_max3_f32 v1, v1, v52, v53
	v_max3_f32 v108, v108, v54, v55
	v_max3_f32 v110, v110, v56, v57
	v_max3_f32 v114, v114, v58, v59
	v_max3_f32 v1, v1, v60, v61
	v_max3_f32 v108, v108, v62, v63
	v_max3_f32 v110, v110, v64, v65
	v_max3_f32 v1, v1, v114, s82
	v_max3_f32 v1, v1, v108, v110
	v_mov_b32_e32 v108, v1
	s_nop 1
	v_permlane32_swap_b32_e32 v108, v1
	v_max_f32_e32 v1, v1, v108
	s_and_saveexec_b64 s[12:13], s[10:11]
	s_xor_b64 s[10:11], exec, s[12:13]
	s_cbranch_execnz .LBB0_934
	s_or_saveexec_b64 s[12:13], s[10:11]
	s_mov_b64 s[10:11], 0
	s_xor_b64 exec, exec, s[12:13]
	s_cbranch_execnz .LBB0_937

.LBB0_925:
	v_exp_f32_e32 v34, v34
	v_exp_f32_e32 v35, v35
	v_exp_f32_e32 v36, v36
	v_exp_f32_e32 v37, v37
	v_exp_f32_e32 v38, v38
	v_exp_f32_e32 v39, v39
	v_exp_f32_e32 v40, v40
	v_exp_f32_e32 v41, v41
	v_add_f32_e32 v108, v34, v35
	v_add_f32_e32 v110, v36, v37
	v_add_f32_e32 v108, v108, v38
	v_add_f32_e32 v110, v110, v39
	v_add_f32_e32 v108, v108, v40
	v_add_f32_e32 v110, v110, v41
	v_cvt_pk_bf16_f32 v148, v34, v35
	v_cvt_pk_bf16_f32 v149, v36, v37
	v_cvt_pk_bf16_f32 v150, v38, v39
	v_cvt_pk_bf16_f32 v151, v40, v41
	v_exp_f32_e32 v42, v42
	v_exp_f32_e32 v43, v43
	s_waitcnt lgkmcnt(0)
	v_mfma_f32_32x32x16_bf16 v[18:33], v[198:201], v[148:151], v[18:33]
	v_mfma_f32_32x32x16_bf16 v[2:17], v[214:217], v[148:151], v[2:17]
	v_exp_f32_e32 v44, v44
	v_exp_f32_e32 v45, v45
	v_exp_f32_e32 v46, v46
	v_exp_f32_e32 v47, v47
	v_exp_f32_e32 v48, v48
	v_exp_f32_e32 v49, v49
	v_add_f32_e32 v108, v108, v42
	v_add_f32_e32 v110, v110, v43
	v_add_f32_e32 v108, v108, v44
	v_add_f32_e32 v110, v110, v45
	v_add_f32_e32 v108, v108, v46
	v_add_f32_e32 v110, v110, v47
	v_add_f32_e32 v108, v108, v48
	v_add_f32_e32 v110, v110, v49
	v_cvt_pk_bf16_f32 v156, v42, v43
	v_cvt_pk_bf16_f32 v157, v44, v45
	v_cvt_pk_bf16_f32 v158, v46, v47
	v_cvt_pk_bf16_f32 v159, v48, v49
	v_exp_f32_e32 v50, v50
	v_exp_f32_e32 v51, v51
	v_mfma_f32_32x32x16_bf16 v[18:33], v[202:205], v[156:159], v[18:33]
	v_mfma_f32_32x32x16_bf16 v[2:17], v[218:221], v[156:159], v[2:17]
	v_exp_f32_e32 v52, v52
	v_exp_f32_e32 v53, v53
	v_exp_f32_e32 v54, v54
	v_exp_f32_e32 v55, v55
	v_exp_f32_e32 v56, v56
	v_exp_f32_e32 v57, v57
	v_add_f32_e32 v108, v108, v50
	v_add_f32_e32 v110, v110, v51
	v_add_f32_e32 v108, v108, v52
	v_add_f32_e32 v110, v110, v53
	v_add_f32_e32 v108, v108, v54
	v_add_f32_e32 v110, v110, v55
	v_add_f32_e32 v108, v108, v56
	v_add_f32_e32 v110, v110, v57
	v_cvt_pk_bf16_f32 v172, v50, v51
	v_cvt_pk_bf16_f32 v173, v52, v53
	v_cvt_pk_bf16_f32 v174, v54, v55
	v_cvt_pk_bf16_f32 v175, v56, v57
	v_exp_f32_e32 v58, v58
	v_exp_f32_e32 v59, v59
	v_mfma_f32_32x32x16_bf16 v[18:33], v[206:209], v[172:175], v[18:33]
	v_mfma_f32_32x32x16_bf16 v[2:17], v[234:237], v[172:175], v[2:17]
	v_exp_f32_e32 v60, v60
	v_exp_f32_e32 v61, v61
	v_exp_f32_e32 v62, v62
	v_exp_f32_e32 v63, v63
	v_exp_f32_e32 v64, v64
	v_exp_f32_e32 v65, v65
	v_add_f32_e32 v108, v108, v58
	v_add_f32_e32 v110, v110, v59
	v_add_f32_e32 v108, v108, v60
	v_add_f32_e32 v110, v110, v61
	v_add_f32_e32 v108, v108, v62
	v_add_f32_e32 v110, v110, v63
	v_add_f32_e32 v108, v108, v64
	v_add_f32_e32 v110, v110, v65
	v_cvt_pk_bf16_f32 v246, v58, v59
	v_cvt_pk_bf16_f32 v247, v60, v61
	v_cvt_pk_bf16_f32 v248, v62, v63
	v_cvt_pk_bf16_f32 v249, v64, v65
	v_add_f32_e32 v108, v108, v110
	v_add_f32_e32 v111, v111, v108
	v_mfma_f32_32x32x16_bf16 v[18:33], v[210:213], v[246:249], v[18:33]
	v_mfma_f32_32x32x16_bf16 v[2:17], v[238:241], v[246:249], v[2:17]
; #define LAS __attribute__((address_space(3)))
; #define STAGE_TILE(bufi, KR, VR) do { LAS bf16_t* Ks_ = (LAS bf16_t*)(lds + (bufi) * 18432); LAS bf16_t* Vs_ = (LAS bf16_t*)(lds + (bufi) * 18432 + 9216); \
;         *(LAS u32x4*)(Ks_ + skr * 72 + sch * 8) = KR; *(LAS u32x4*)(Vs_ + skr * 72 + sch * 8) = VR; } while (0)
; #define LOAD_TILE(KR, VR, tl) do { KR = *(const GAS u32x4*)(kg + (size_t)(tl) * 64 * LDH); VR = *(const GAS u32x4*)(vg + (size_t)(tl) * 64 * LDH); } while (0)
; template <int MODE> ...
;     ...
;         STAGE_TILE(1, kB, vB);
;         __syncthreads();
;         if (MODE == 1) { const u32x4 fa = *(const LAS u32x4*)flags, fb = *(const LAS u32x4*)(flags + 4); if ((fa.x & fa.y & fa.z & fa.w & fb.x & fb.y & fb.z & fb.w) != 0u) break; }
;         LOAD_TILE(kB, vB, TILE_OF(min(it + 3, ntiles - 1)));
;         COMPUTE_TILE(TILE_OF(it + 1), 1);
.LBB0_926:
	s_add_i32 s12, s23, 3
	s_min_i32 s14, s12, s18
	s_mul_i32 s12, s14, 0x62000
	s_mov_b32 s13, 0
	v_lshl_add_u64 v[34:35], s[12:13], 0, v[102:103]
	s_waitcnt vmcnt(3)
	ds_write_b128 v101, v[82:85] offset:18432
	s_waitcnt vmcnt(2)
	ds_write_b128 v101, v[86:89] offset:27648
	s_waitcnt lgkmcnt(0)
	s_barrier
	s_mul_i32 s12, s14, 0x62000
	s_mov_b32 s13, 0
	v_lshl_add_u64 v[36:37], s[12:13], 0, v[104:105]
	global_load_dwordx4 v[82:85], v[34:35], off
	global_load_dwordx4 v[86:89], v[36:37], off
	s_cmp_ge_i32 s23, s17
	s_cbranch_scc1 .LBB0_932
	ds_read_b64 v[34:35], v109 offset:8
	ds_read_b128 v[118:121], v113 offset:18432
	ds_read_b128 v[122:125], v113 offset:18464
	ds_read_b128 v[126:129], v113 offset:18496
	ds_read_b128 v[130:133], v113 offset:18528
	ds_read_b128 v[182:185], v113 offset:23040
	ds_read_b128 v[186:189], v113 offset:23072
	ds_read_b128 v[190:193], v113 offset:23104
	ds_read_b128 v[242:245], v113 offset:23136
	v_sub_f32_e32 v1, 0, v112
	s_xor_b64 s[10:11], s[10:11], -1
	s_waitcnt lgkmcnt(8)
	v_lshrrev_b64 v[114:115], v100, v[34:35]
	v_lshrrev_b64 v[116:117], v106, v[34:35]
	v_bfe_i32 v34, v114, 0, 1
	v_bfe_i32 v35, v114, 1, 1
	v_bfe_i32 v36, v114, 2, 1
	v_bfe_i32 v37, v114, 3, 1
	v_bfe_i32 v38, v114, 8, 1
	v_bfe_i32 v39, v114, 9, 1
	v_bfe_i32 v40, v114, 10, 1
	v_bfe_i32 v41, v114, 11, 1
	v_bfe_i32 v42, v114, 16, 1
	v_bfe_i32 v43, v114, 17, 1
	v_bfe_i32 v44, v114, 18, 1
	v_bfe_i32 v45, v114, 19, 1
	v_bfe_i32 v46, v114, 24, 1
	v_bfe_i32 v47, v114, 25, 1
	v_bfe_i32 v48, v114, 26, 1
	v_bfe_i32 v49, v114, 27, 1
	v_bfi_b32 v34, v34, v1, v232
	v_bfi_b32 v35, v35, v1, v232
	v_bfi_b32 v36, v36, v1, v232
	v_bfi_b32 v37, v37, v1, v232
	v_bfi_b32 v38, v38, v1, v232
	v_bfi_b32 v39, v39, v1, v232
	v_bfi_b32 v40, v40, v1, v232
	v_bfi_b32 v41, v41, v1, v232
	v_bfi_b32 v42, v42, v1, v232
	v_bfi_b32 v43, v43, v1, v232
	v_bfi_b32 v44, v44, v1, v232
	v_bfi_b32 v45, v45, v1, v232
	v_bfi_b32 v46, v46, v1, v232
	v_bfi_b32 v47, v47, v1, v232
	v_bfi_b32 v48, v48, v1, v232
	v_bfi_b32 v49, v49, v1, v232
	s_waitcnt lgkmcnt(4)
	s_nop 0
	v_mfma_f32_32x32x16_bf16 v[34:49], v[118:121], v[74:77], v[34:49]
	v_bfe_i32 v50, v116, 0, 1
	v_bfe_i32 v51, v116, 1, 1
	v_bfe_i32 v52, v116, 2, 1
	v_bfe_i32 v53, v116, 3, 1
	v_bfe_i32 v54, v116, 8, 1
	v_bfe_i32 v55, v116, 9, 1
	v_bfe_i32 v56, v116, 10, 1
	v_bfe_i32 v57, v116, 11, 1
	s_waitcnt lgkmcnt(4)
	v_mfma_f32_32x32x16_bf16 v[34:49], v[122:125], v[66:69], v[34:49]
	v_bfe_i32 v58, v116, 16, 1
	v_bfe_i32 v59, v116, 17, 1
	v_bfe_i32 v60, v116, 18, 1
	v_bfe_i32 v61, v116, 19, 1
	v_bfe_i32 v62, v116, 24, 1
	v_bfe_i32 v63, v116, 25, 1
	v_bfe_i32 v64, v116, 26, 1
	v_bfe_i32 v65, v116, 27, 1
	s_waitcnt lgkmcnt(4)
	v_mfma_f32_32x32x16_bf16 v[34:49], v[126:129], v[70:73], v[34:49]
	v_bfi_b32 v50, v50, v1, v232
	v_bfi_b32 v51, v51, v1, v232
	v_bfi_b32 v52, v52, v1, v232
	v_bfi_b32 v53, v53, v1, v232
	v_bfi_b32 v54, v54, v1, v232
	v_bfi_b32 v55, v55, v1, v232
	v_bfi_b32 v56, v56, v1, v232
	v_bfi_b32 v57, v57, v1, v232
	s_waitcnt lgkmcnt(0)
	v_mfma_f32_32x32x16_bf16 v[34:49], v[130:133], v[78:81], v[34:49]
	v_bfi_b32 v58, v58, v1, v232
	v_bfi_b32 v59, v59, v1, v232
	v_bfi_b32 v60, v60, v1, v232
	v_bfi_b32 v61, v61, v1, v232
	v_bfi_b32 v62, v62, v1, v232
	v_bfi_b32 v63, v63, v1, v232
	v_bfi_b32 v64, v64, v1, v232
	v_bfi_b32 v65, v65, v1, v232
	s_nop 1
	v_mfma_f32_32x32x16_bf16 v[50:65], v[182:185], v[74:77], v[50:65]
	ds_read_b64_tr_b16 v[198:199], v107 offset:27648
	ds_read_b64_tr_b16 v[200:201], v107 offset:28800
	ds_read_b64_tr_b16 v[202:203], v107 offset:29952
	ds_read_b64_tr_b16 v[204:205], v107 offset:31104
	v_mfma_f32_32x32x16_bf16 v[50:65], v[186:189], v[66:69], v[50:65]
	ds_read_b64_tr_b16 v[206:207], v107 offset:32256
	ds_read_b64_tr_b16 v[208:209], v107 offset:33408
	ds_read_b64_tr_b16 v[210:211], v107 offset:34560
	ds_read_b64_tr_b16 v[212:213], v107 offset:35712
	v_mfma_f32_32x32x16_bf16 v[50:65], v[190:193], v[70:73], v[50:65]
	ds_read_b64_tr_b16 v[214:215], v107 offset:27712
	ds_read_b64_tr_b16 v[216:217], v107 offset:28864
	ds_read_b64_tr_b16 v[218:219], v107 offset:30016
	ds_read_b64_tr_b16 v[220:221], v107 offset:31168
	v_mfma_f32_32x32x16_bf16 v[50:65], v[242:245], v[78:81], v[50:65]
	ds_read_b64_tr_b16 v[234:235], v107 offset:32320
	ds_read_b64_tr_b16 v[236:237], v107 offset:33472
	ds_read_b64_tr_b16 v[238:239], v107 offset:34624
	ds_read_b64_tr_b16 v[240:241], v107 offset:35776
	s_nop 1
	v_max3_f32 v108, v34, v35, v36
	v_max3_f32 v110, v37, v38, v39
	v_max3_f32 v114, v40, v41, v42
	v_max3_f32 v1, v43, v44, v45
	v_max3_f32 v108, v108, v46, v47
	v_max3_f32 v110, v110, v48, v49
	v_max3_f32 v114, v114, v50, v51
	v_max3_f32 v1, v1, v52, v53
	v_max3_f32 v108, v108, v54, v55
	v_max3_f32 v110, v110, v56, v57
	v_max3_f32 v114, v114, v58, v59
	v_max3_f32 v1, v1, v60, v61
	v_max3_f32 v108, v108, v62, v63
	v_max3_f32 v110, v110, v64, v65
	v_max3_f32 v1, v1, v114, s82
	v_max3_f32 v1, v1, v108, v110
	v_mov_b32_e32 v108, v1
	s_nop 1
	v_permlane32_swap_b32_e32 v108, v1
	v_max_f32_e32 v1, v1, v108
	s_and_saveexec_b64 s[12:13], s[10:11]
	s_xor_b64 s[10:11], exec, s[12:13]
	s_cbranch_execnz .LBB0_940
	s_or_saveexec_b64 s[12:13], s[10:11]
	s_mov_b64 s[10:11], 0
	s_xor_b64 exec, exec, s[12:13]
	s_cbranch_execnz .LBB0_943
